# static priority raise for waves 0-3 instead (opposite half), no per-segment toggling
# speedup vs baseline: 1.0055x; 1.0055x over previous
.LBB0_7:
	v_cmp_lt_u32_e32 vcc, 0xff, v0
	s_setprio 1
	s_cbranch_vccz .Lprio_lo
	s_setprio 0
